# P2 arrival guard pre-checked in the P1|P2 seam poll: the last-arriving (critical) teams see all 256 arrivals there and skip the later poll
# baseline (speedup 1.0000x reference)
; #define LAS __attribute__((address_space(3)))
; __global__ void __launch_bounds__(NWAVES * 64, 2) fwd(Args args) {
;     extern __shared__ __attribute__((aligned(16))) unsigned char lds_raw[];
;     LAS unsigned char* lds = (LAS unsigned char*)lds_raw;
;     volatile LAS unsigned* MISC = (volatile LAS unsigned*)(lds + MISC_OFF);
;     const int tid = threadIdx.x, lane = tid & 63, wave = __builtin_amdgcn_readfirstlane(tid >> 6);
;     const int G = gridDim.x; const int bx = blockIdx.x; const int vcu = (G % 8 == 0) ? (bx % 8) * (G / 8) + bx / 8 : bx;
_Z3fwd4Args:
	s_mov_b32 s100, 0
	s_load_dword s34, s[0:1], 0xa8
	s_add_u32 s4, s0, 0xa8
	s_addc_u32 s5, s1, 0
	v_readfirstlane_b32 s66, v0
	v_writelane_b32 v240, s4, 0
	s_waitcnt lgkmcnt(0)
	s_and_b32 s3, s34, 7
	s_cmp_lg_u32 s3, 0
	s_mov_b32 s8, s2
	v_writelane_b32 v240, s5, 1
	s_cbranch_scc1 .LBB0_2
	s_ashr_i32 s4, s2, 31
	s_lshr_b32 s4, s4, 29
	s_add_i32 s4, s2, s4
	s_and_b32 s5, s4, -8
	s_ashr_i32 s3, s34, 3
	s_sub_i32 s5, s2, s5
	s_mul_i32 s3, s3, s5
	s_ashr_i32 s4, s4, 3
	s_add_i32 s8, s3, s4

; __device__ __forceinline__ unsigned xb_ld(unsigned* p)              { return __hip_atomic_load(p, __ATOMIC_RELAXED, __HIP_MEMORY_SCOPE_AGENT); }
; __device__ __forceinline__ unsigned xb_add(unsigned* p, unsigned v) { return __hip_atomic_fetch_add(p, v, __ATOMIC_RELAXED, __HIP_MEMORY_SCOPE_AGENT); }
; #define XB_SPIN(cond, bar) do { unsigned _sp = 0; while (cond) { __builtin_amdgcn_s_sleep(1); \
;     if ((++_sp & 255u) == 0u) { if (xb_ld(&(bar)[XB_TMO])) break; if (_sp > XB_SPIN_CAP) { atomicAdd(&(bar)[XB_TMO], 1u); break; } } } } while (0)
; __device__ __forceinline__ void team_barrier(unsigned* ctr, unsigned target, unsigned* bar) {
;     asm volatile("s_waitcnt vmcnt(0)" ::: "memory");
;     __syncthreads();
;     if (threadIdx.x == 0) {
;         __builtin_amdgcn_s_waitcnt(0);
;         (void)xb_add(ctr, 1u);
;         asm volatile("buffer_inv sc1" ::: "memory");
;         XB_SPIN(xb_ld(ctr) < target, bar);
;         asm volatile("s_waitcnt vmcnt(0)" ::: "memory");
;     }
;     __syncthreads();
; }
.Lts1_spin:
	global_load_dword v6, v1, s[8:9] sc1
	global_load_dword v7, v1, s[10:11] sc1
	global_load_dword v8, v3, s[60:61] sc1
	s_waitcnt vmcnt(0)
	v_min_u32_e32 v6, v6, v7
	v_cmp_lt_u32_e32 vcc, 3, v6
	s_cbranch_vccnz .Lts1_done
	s_sleep 1
	v_add_u32_e32 v5, 1, v5
	v_cmp_gt_u32_e32 vcc, 0x4000, v5
	s_cbranch_vccnz .Lts1_spin
	global_atomic_add v1, v2, s[58:59] offset:512
.Lts1_done:
	buffer_inv sc1
	v_readfirstlane_b32 s100, v8
	s_waitcnt vmcnt(0)

; #define LAS __attribute__((address_space(3)))
; __device__ __forceinline__ unsigned long long rt() { return __builtin_amdgcn_s_memrealtime(); }
; __global__ void __launch_bounds__(NWAVES * 64, 2) fwd(Args args) {
;     ...
;     if (IN(2)) {
;         const unsigned long long amp_t0_2 = (PROBE_AMP == 2 || PROBE_AMP == 21) ? rt() : 0ull;
;         {
;             { const int h_ = (int)blockIdx.x & 3; LAS float* cw = (LAS float*)(lds + CONVW_OFF);
;               for (int i = tid; i < 1536; i += NWAVES * 64) { const int part = i >> 9, j = (i >> 7) & 3, cc = i & 127; cw[i] = args.in[3][j * 1536 + part * 512 + h_ * 128 + cc]; } }
;             DnRaw R; dn_load_raw(R, (int)blockIdx.x, DNR, HALO, GBT, tid);
;             { HgRaw H; hg_load_raw(H, HGR + (size_t)blockIdx.x * 32768, tid);
;               for (int u = (int)blockIdx.x; u < 1024; u += G) p2_hg_unit(lds, HGR + (size_t)u * 32768, OLH + (size_t)u * 8192, DEC + (size_t)u * 128, tid, lane, wave, H, (u + G < 1024) ? HGR + (size_t)(u + G) * 32768 : nullptr); }
.LBB0_423:
	s_cmpk_gt_u32 s2, 0xbf
	s_cbranch_scc1 .Lts1_gskip
	s_and_saveexec_b64 s[6:7], s[96:97]
	s_cbranch_execz .Lts1_gjoin
	s_cmpk_gt_u32 s100, 0xff
	s_cbranch_scc1 .Lts1_gjoin
	v_mov_b32_e32 v68, 0x2c000
	v_mov_b32_e32 v70, 0
